# phase_small_from_xn tile loop: all 32 XN fragment loads of a tile in flight at once (was ~2 in flight), LDS weight fragments double-buffered
# baseline (speedup 1.0000x reference)
.LBB0_1561:
	s_nop 0
	v_add_u32_e32 v0, s5, v11
	v_ashrrev_i32_e32 v1, 31, v0
	v_lshlrev_b64 v[0:1], 11, v[0:1]
	v_lshl_add_u64 v[0:1], v[6:7], 0, v[0:1]
	v_mov_b32_e32 v32, v10
	global_load_dwordx4 v[100:103], v[0:1], off
	global_load_dwordx4 v[104:107], v[0:1], off offset:64
	global_load_dwordx4 v[108:111], v[0:1], off offset:128
	global_load_dwordx4 v[112:115], v[0:1], off offset:192
	global_load_dwordx4 v[116:119], v[0:1], off offset:256
	global_load_dwordx4 v[120:123], v[0:1], off offset:320
	global_load_dwordx4 v[124:127], v[0:1], off offset:384
	global_load_dwordx4 v[128:131], v[0:1], off offset:448
	global_load_dwordx4 v[132:135], v[0:1], off offset:512
	global_load_dwordx4 v[136:139], v[0:1], off offset:576
	global_load_dwordx4 v[140:143], v[0:1], off offset:640
	global_load_dwordx4 v[144:147], v[0:1], off offset:704
	global_load_dwordx4 v[148:151], v[0:1], off offset:768
	global_load_dwordx4 v[152:155], v[0:1], off offset:832
	global_load_dwordx4 v[156:159], v[0:1], off offset:896
	global_load_dwordx4 v[160:163], v[0:1], off offset:960
	global_load_dwordx4 v[164:167], v[0:1], off offset:1024
	global_load_dwordx4 v[168:171], v[0:1], off offset:1088
	global_load_dwordx4 v[172:175], v[0:1], off offset:1152
	global_load_dwordx4 v[176:179], v[0:1], off offset:1216
	global_load_dwordx4 v[180:183], v[0:1], off offset:1280
	global_load_dwordx4 v[184:187], v[0:1], off offset:1344
	global_load_dwordx4 v[188:191], v[0:1], off offset:1408
	global_load_dwordx4 v[192:195], v[0:1], off offset:1472
	global_load_dwordx4 v[196:199], v[0:1], off offset:1536
	global_load_dwordx4 v[200:203], v[0:1], off offset:1600
	global_load_dwordx4 v[204:207], v[0:1], off offset:1664
	global_load_dwordx4 v[208:211], v[0:1], off offset:1728
	global_load_dwordx4 v[212:215], v[0:1], off offset:1792
	global_load_dwordx4 v[216:219], v[0:1], off offset:1856
	global_load_dwordx4 v[220:223], v[0:1], off offset:1920
	global_load_dwordx4 v[224:227], v[0:1], off offset:1984
	v_add_u32_e32 v33, 0x10000, v10
	v_add_u32_e32 v34, 0x18100, v10
	ds_read_b128 v[20:23], v33
	ds_read_b128 v[24:27], v34
	ds_read_b128 v[36:39], v33 offset:64
	ds_read_b128 v[40:43], v34 offset:64
	s_waitcnt vmcnt(31) lgkmcnt(2)
	v_mfma_f32_16x16x32_bf16 v[12:15], v[100:103], v[20:23], 0
	v_mfma_f32_16x16x32_bf16 v[12:15], v[100:103], v[24:27], v[12:15]
	ds_read_b128 v[20:23], v33 offset:128
	ds_read_b128 v[24:27], v34 offset:128
	s_waitcnt vmcnt(30) lgkmcnt(2)
	v_mfma_f32_16x16x32_bf16 v[12:15], v[104:107], v[36:39], v[12:15]
	v_mfma_f32_16x16x32_bf16 v[12:15], v[104:107], v[40:43], v[12:15]
	ds_read_b128 v[36:39], v33 offset:192
	ds_read_b128 v[40:43], v34 offset:192
	s_waitcnt vmcnt(29) lgkmcnt(2)
	v_mfma_f32_16x16x32_bf16 v[12:15], v[108:111], v[20:23], v[12:15]
	v_mfma_f32_16x16x32_bf16 v[12:15], v[108:111], v[24:27], v[12:15]
	ds_read_b128 v[20:23], v33 offset:256
	ds_read_b128 v[24:27], v34 offset:256
	s_waitcnt vmcnt(28) lgkmcnt(2)
	v_mfma_f32_16x16x32_bf16 v[12:15], v[112:115], v[36:39], v[12:15]
	v_mfma_f32_16x16x32_bf16 v[12:15], v[112:115], v[40:43], v[12:15]
	ds_read_b128 v[36:39], v33 offset:320
	ds_read_b128 v[40:43], v34 offset:320
	s_waitcnt vmcnt(27) lgkmcnt(2)
	v_mfma_f32_16x16x32_bf16 v[12:15], v[116:119], v[20:23], v[12:15]
	v_mfma_f32_16x16x32_bf16 v[12:15], v[116:119], v[24:27], v[12:15]
	ds_read_b128 v[20:23], v33 offset:384
	ds_read_b128 v[24:27], v34 offset:384
	s_waitcnt vmcnt(26) lgkmcnt(2)
	v_mfma_f32_16x16x32_bf16 v[12:15], v[120:123], v[36:39], v[12:15]
	v_mfma_f32_16x16x32_bf16 v[12:15], v[120:123], v[40:43], v[12:15]
	ds_read_b128 v[36:39], v33 offset:448
	ds_read_b128 v[40:43], v34 offset:448
	s_waitcnt vmcnt(25) lgkmcnt(2)
	v_mfma_f32_16x16x32_bf16 v[12:15], v[124:127], v[20:23], v[12:15]
	v_mfma_f32_16x16x32_bf16 v[12:15], v[124:127], v[24:27], v[12:15]
	ds_read_b128 v[20:23], v33 offset:512
	ds_read_b128 v[24:27], v34 offset:512
	s_waitcnt vmcnt(24) lgkmcnt(2)
	v_mfma_f32_16x16x32_bf16 v[12:15], v[128:131], v[36:39], v[12:15]
	v_mfma_f32_16x16x32_bf16 v[12:15], v[128:131], v[40:43], v[12:15]
	ds_read_b128 v[36:39], v33 offset:576
	ds_read_b128 v[40:43], v34 offset:576
	s_waitcnt vmcnt(23) lgkmcnt(2)
	v_mfma_f32_16x16x32_bf16 v[12:15], v[132:135], v[20:23], v[12:15]
	v_mfma_f32_16x16x32_bf16 v[12:15], v[132:135], v[24:27], v[12:15]
	ds_read_b128 v[20:23], v33 offset:640
	ds_read_b128 v[24:27], v34 offset:640
	s_waitcnt vmcnt(22) lgkmcnt(2)
	v_mfma_f32_16x16x32_bf16 v[12:15], v[136:139], v[36:39], v[12:15]
	v_mfma_f32_16x16x32_bf16 v[12:15], v[136:139], v[40:43], v[12:15]
	ds_read_b128 v[36:39], v33 offset:704
	ds_read_b128 v[40:43], v34 offset:704
	s_waitcnt vmcnt(21) lgkmcnt(2)
	v_mfma_f32_16x16x32_bf16 v[12:15], v[140:143], v[20:23], v[12:15]
	v_mfma_f32_16x16x32_bf16 v[12:15], v[140:143], v[24:27], v[12:15]
	ds_read_b128 v[20:23], v33 offset:768
	ds_read_b128 v[24:27], v34 offset:768
	s_waitcnt vmcnt(20) lgkmcnt(2)
	v_mfma_f32_16x16x32_bf16 v[12:15], v[144:147], v[36:39], v[12:15]
	v_mfma_f32_16x16x32_bf16 v[12:15], v[144:147], v[40:43], v[12:15]
	ds_read_b128 v[36:39], v33 offset:832
	ds_read_b128 v[40:43], v34 offset:832
	s_waitcnt vmcnt(19) lgkmcnt(2)
	v_mfma_f32_16x16x32_bf16 v[12:15], v[148:151], v[20:23], v[12:15]
	v_mfma_f32_16x16x32_bf16 v[12:15], v[148:151], v[24:27], v[12:15]
	ds_read_b128 v[20:23], v33 offset:896
	ds_read_b128 v[24:27], v34 offset:896
	s_waitcnt vmcnt(18) lgkmcnt(2)
	v_mfma_f32_16x16x32_bf16 v[12:15], v[152:155], v[36:39], v[12:15]
	v_mfma_f32_16x16x32_bf16 v[12:15], v[152:155], v[40:43], v[12:15]
	ds_read_b128 v[36:39], v33 offset:960
	ds_read_b128 v[40:43], v34 offset:960
	s_waitcnt vmcnt(17) lgkmcnt(2)
	v_mfma_f32_16x16x32_bf16 v[12:15], v[156:159], v[20:23], v[12:15]
	v_mfma_f32_16x16x32_bf16 v[12:15], v[156:159], v[24:27], v[12:15]
	ds_read_b128 v[20:23], v33 offset:1024
	ds_read_b128 v[24:27], v34 offset:1024
	s_waitcnt vmcnt(16) lgkmcnt(2)
	v_mfma_f32_16x16x32_bf16 v[12:15], v[160:163], v[36:39], v[12:15]
	v_mfma_f32_16x16x32_bf16 v[12:15], v[160:163], v[40:43], v[12:15]
	ds_read_b128 v[36:39], v33 offset:1088
	ds_read_b128 v[40:43], v34 offset:1088
	s_waitcnt vmcnt(15) lgkmcnt(2)
	v_mfma_f32_16x16x32_bf16 v[12:15], v[164:167], v[20:23], v[12:15]
	v_mfma_f32_16x16x32_bf16 v[12:15], v[164:167], v[24:27], v[12:15]
	ds_read_b128 v[20:23], v33 offset:1152
	ds_read_b128 v[24:27], v34 offset:1152
	s_waitcnt vmcnt(14) lgkmcnt(2)
	v_mfma_f32_16x16x32_bf16 v[12:15], v[168:171], v[36:39], v[12:15]
	v_mfma_f32_16x16x32_bf16 v[12:15], v[168:171], v[40:43], v[12:15]
	ds_read_b128 v[36:39], v33 offset:1216
	ds_read_b128 v[40:43], v34 offset:1216
	s_waitcnt vmcnt(13) lgkmcnt(2)
	v_mfma_f32_16x16x32_bf16 v[12:15], v[172:175], v[20:23], v[12:15]
	v_mfma_f32_16x16x32_bf16 v[12:15], v[172:175], v[24:27], v[12:15]
	ds_read_b128 v[20:23], v33 offset:1280
	ds_read_b128 v[24:27], v34 offset:1280
	s_waitcnt vmcnt(12) lgkmcnt(2)
	v_mfma_f32_16x16x32_bf16 v[12:15], v[176:179], v[36:39], v[12:15]
	v_mfma_f32_16x16x32_bf16 v[12:15], v[176:179], v[40:43], v[12:15]
	ds_read_b128 v[36:39], v33 offset:1344
	ds_read_b128 v[40:43], v34 offset:1344
	s_waitcnt vmcnt(11) lgkmcnt(2)
	v_mfma_f32_16x16x32_bf16 v[12:15], v[180:183], v[20:23], v[12:15]
	v_mfma_f32_16x16x32_bf16 v[12:15], v[180:183], v[24:27], v[12:15]
	ds_read_b128 v[20:23], v33 offset:1408
	ds_read_b128 v[24:27], v34 offset:1408
	s_waitcnt vmcnt(10) lgkmcnt(2)
	v_mfma_f32_16x16x32_bf16 v[12:15], v[184:187], v[36:39], v[12:15]
	v_mfma_f32_16x16x32_bf16 v[12:15], v[184:187], v[40:43], v[12:15]
	ds_read_b128 v[36:39], v33 offset:1472
	ds_read_b128 v[40:43], v34 offset:1472
	s_waitcnt vmcnt(9) lgkmcnt(2)
	v_mfma_f32_16x16x32_bf16 v[12:15], v[188:191], v[20:23], v[12:15]
	v_mfma_f32_16x16x32_bf16 v[12:15], v[188:191], v[24:27], v[12:15]
	ds_read_b128 v[20:23], v33 offset:1536
	ds_read_b128 v[24:27], v34 offset:1536
	s_waitcnt vmcnt(8) lgkmcnt(2)
	v_mfma_f32_16x16x32_bf16 v[12:15], v[192:195], v[36:39], v[12:15]
	v_mfma_f32_16x16x32_bf16 v[12:15], v[192:195], v[40:43], v[12:15]
	ds_read_b128 v[36:39], v33 offset:1600
	ds_read_b128 v[40:43], v34 offset:1600
	s_waitcnt vmcnt(7) lgkmcnt(2)
	v_mfma_f32_16x16x32_bf16 v[12:15], v[196:199], v[20:23], v[12:15]
	v_mfma_f32_16x16x32_bf16 v[12:15], v[196:199], v[24:27], v[12:15]
	ds_read_b128 v[20:23], v33 offset:1664
	ds_read_b128 v[24:27], v34 offset:1664
	s_waitcnt vmcnt(6) lgkmcnt(2)
	v_mfma_f32_16x16x32_bf16 v[12:15], v[200:203], v[36:39], v[12:15]
	v_mfma_f32_16x16x32_bf16 v[12:15], v[200:203], v[40:43], v[12:15]
	ds_read_b128 v[36:39], v33 offset:1728
	ds_read_b128 v[40:43], v34 offset:1728
	s_waitcnt vmcnt(5) lgkmcnt(2)
	v_mfma_f32_16x16x32_bf16 v[12:15], v[204:207], v[20:23], v[12:15]
	v_mfma_f32_16x16x32_bf16 v[12:15], v[204:207], v[24:27], v[12:15]
	ds_read_b128 v[20:23], v33 offset:1792
	ds_read_b128 v[24:27], v34 offset:1792
	s_waitcnt vmcnt(4) lgkmcnt(2)
	v_mfma_f32_16x16x32_bf16 v[12:15], v[208:211], v[36:39], v[12:15]
	v_mfma_f32_16x16x32_bf16 v[12:15], v[208:211], v[40:43], v[12:15]
	ds_read_b128 v[36:39], v33 offset:1856
	ds_read_b128 v[40:43], v34 offset:1856
	s_waitcnt vmcnt(3) lgkmcnt(2)
	v_mfma_f32_16x16x32_bf16 v[12:15], v[212:215], v[20:23], v[12:15]
	v_mfma_f32_16x16x32_bf16 v[12:15], v[212:215], v[24:27], v[12:15]
	ds_read_b128 v[20:23], v33 offset:1920
	ds_read_b128 v[24:27], v34 offset:1920
	s_waitcnt vmcnt(2) lgkmcnt(2)
	v_mfma_f32_16x16x32_bf16 v[12:15], v[216:219], v[36:39], v[12:15]
	v_mfma_f32_16x16x32_bf16 v[12:15], v[216:219], v[40:43], v[12:15]
	ds_read_b128 v[36:39], v33 offset:1984
	ds_read_b128 v[40:43], v34 offset:1984
	s_waitcnt vmcnt(1) lgkmcnt(2)
	v_mfma_f32_16x16x32_bf16 v[12:15], v[220:223], v[20:23], v[12:15]
	v_mfma_f32_16x16x32_bf16 v[12:15], v[220:223], v[24:27], v[12:15]
	s_waitcnt vmcnt(0) lgkmcnt(0)
	v_mfma_f32_16x16x32_bf16 v[12:15], v[224:227], v[36:39], v[12:15]
	v_mfma_f32_16x16x32_bf16 v[0:3], v[224:227], v[40:43], v[12:15]
	s_and_saveexec_b64 s[2:3], vcc
	s_cbranch_execz .LBB0_1560
	s_nop 3
	v_add_u32_e32 v14, s5, v5
	v_add_u32_e32 v12, -16, v14
	v_ashrrev_i32_e32 v13, 31, v12
	v_lshlrev_b64 v[12:13], 6, v[12:13]
	v_lshl_add_u64 v[12:13], v[8:9], 0, v[12:13]
	global_store_dword v[12:13], v0, off
	v_add_u32_e32 v12, -15, v14
	v_ashrrev_i32_e32 v13, 31, v12
	v_lshlrev_b64 v[12:13], 6, v[12:13]
	v_lshl_add_u64 v[12:13], v[8:9], 0, v[12:13]
	v_add_u32_e32 v0, -14, v14
	global_store_dword v[12:13], v1, off
	v_ashrrev_i32_e32 v1, 31, v0
	v_lshlrev_b64 v[0:1], 6, v[0:1]
	v_lshl_add_u64 v[0:1], v[8:9], 0, v[0:1]
	global_store_dword v[0:1], v2, off
	v_add_u32_e32 v0, -13, v14
	v_ashrrev_i32_e32 v1, 31, v0
	v_lshlrev_b64 v[0:1], 6, v[0:1]
	v_lshl_add_u64 v[0:1], v[8:9], 0, v[0:1]
	global_store_dword v[0:1], v3, off
	s_branch .LBB0_1560
